# attention: cross-half max exchange via v_permlane32_swap instead of ds_bpermute + lazy max + previous
# speedup vs baseline: 1.0061x; 1.0018x over previous
.LBB0_659:
	s_waitcnt vmcnt(4)
	v_add3_u32 v124, 0, v169, v170
	ds_read_b128 v[32:35], v124
	s_waitcnt vmcnt(3)
	ds_read_b128 v[120:123], v124 offset:32
	s_waitcnt lgkmcnt(1)
	v_mfma_f32_32x32x16_bf16 v[80:95], v[32:35], v[108:111], v[194:209]
	ds_read_b128 v[32:35], v124 offset:6656
	s_waitcnt lgkmcnt(1)
	v_mfma_f32_32x32x16_bf16 v[80:95], v[120:123], v[104:107], v[80:95]
	s_waitcnt lgkmcnt(0)
	v_mfma_f32_32x32x16_bf16 v[64:79], v[32:35], v[108:111], v[194:209]
	ds_read_b128 v[32:35], v124 offset:13312
	s_waitcnt lgkmcnt(0)
	v_mfma_f32_32x32x16_bf16 v[48:63], v[32:35], v[108:111], v[194:209]
	ds_read_b128 v[32:35], v124 offset:19968
	s_waitcnt lgkmcnt(0)
	v_mfma_f32_32x32x16_bf16 v[32:47], v[32:35], v[108:111], v[194:209]
	ds_read_b128 v[108:111], v124 offset:6688
	s_waitcnt lgkmcnt(0)
	v_mfma_f32_32x32x16_bf16 v[64:79], v[108:111], v[104:107], v[64:79]
	ds_read_b128 v[108:111], v124 offset:13344
	s_waitcnt lgkmcnt(0)
	v_mfma_f32_32x32x16_bf16 v[48:63], v[108:111], v[104:107], v[48:63]
	ds_read_b128 v[108:111], v124 offset:20000
	s_waitcnt lgkmcnt(0)
	v_mfma_f32_32x32x16_bf16 v[32:47], v[108:111], v[104:107], v[32:47]
	ds_read_b128 v[104:107], v124 offset:64
	s_waitcnt lgkmcnt(0)
	v_mfma_f32_32x32x16_bf16 v[80:95], v[104:107], v[100:103], v[80:95]
	ds_read_b128 v[104:107], v124 offset:6720
	s_waitcnt lgkmcnt(0)
	v_mfma_f32_32x32x16_bf16 v[64:79], v[104:107], v[100:103], v[64:79]
	ds_read_b128 v[104:107], v124 offset:13376
	s_waitcnt lgkmcnt(0)
	v_mfma_f32_32x32x16_bf16 v[48:63], v[104:107], v[100:103], v[48:63]
	ds_read_b128 v[104:107], v124 offset:20032
	s_waitcnt lgkmcnt(0)
	v_mfma_f32_32x32x16_bf16 v[32:47], v[104:107], v[100:103], v[32:47]
	ds_read_b128 v[100:103], v124 offset:96
	s_waitcnt lgkmcnt(0)
	v_mfma_f32_32x32x16_bf16 v[80:95], v[100:103], v[96:99], v[80:95]
	ds_read_b128 v[100:103], v124 offset:6752
	s_waitcnt lgkmcnt(0)
	v_mfma_f32_32x32x16_bf16 v[64:79], v[100:103], v[96:99], v[64:79]
	ds_read_b128 v[100:103], v124 offset:13408
	s_waitcnt lgkmcnt(0)
	v_mfma_f32_32x32x16_bf16 v[48:63], v[100:103], v[96:99], v[48:63]
	ds_read_b128 v[100:103], v124 offset:20064
	s_waitcnt lgkmcnt(0)
	v_mfma_f32_32x32x16_bf16 v[32:47], v[100:103], v[96:99], v[32:47]
	ds_read_b128 v[96:99], v124 offset:128
	s_waitcnt lgkmcnt(0)
	v_mfma_f32_32x32x16_bf16 v[80:95], v[96:99], v[112:115], v[80:95]
	ds_read_b128 v[96:99], v124 offset:6784
	s_waitcnt lgkmcnt(0)
	v_mfma_f32_32x32x16_bf16 v[64:79], v[96:99], v[112:115], v[64:79]
	ds_read_b128 v[96:99], v124 offset:13440
	s_waitcnt lgkmcnt(0)
	v_mfma_f32_32x32x16_bf16 v[48:63], v[96:99], v[112:115], v[48:63]
	ds_read_b128 v[96:99], v124 offset:160
	ds_read_b128 v[100:103], v124 offset:13472
	ds_read_b128 v[104:107], v124 offset:6816
	s_waitcnt lgkmcnt(2)
	v_mfma_f32_32x32x16_bf16 v[80:95], v[96:99], v[116:119], v[80:95]
	ds_read_b128 v[96:99], v124 offset:20128
	ds_read_b128 v[108:111], v124 offset:20096
	s_waitcnt lgkmcnt(2)
	v_mfma_f32_32x32x16_bf16 v[64:79], v[104:107], v[116:119], v[64:79]
	s_nop 7
	v_max_f32_e32 v120, v81, v81
	v_max_f32_e32 v121, v80, v80
	v_max_f32_e32 v120, v121, v120
	v_max3_f32 v120, v120, v82, v83
	v_max3_f32 v120, v120, v84, v85
	v_max3_f32 v104, v120, v86, v87
	v_max3_f32 v104, v104, v88, v89
	v_max3_f32 v104, v104, v90, v91
	v_max3_f32 v104, v104, v92, v93
	v_max3_f32 v104, v104, v94, v95
	v_max3_f32 v104, v104, v64, v65
	v_mfma_f32_32x32x16_bf16 v[48:63], v[100:103], v[116:119], v[48:63]
	v_max3_f32 v104, v104, v66, v67
	v_max3_f32 v100, v104, v68, v69
	v_max3_f32 v100, v100, v70, v71
	v_max3_f32 v100, v100, v72, v73
	v_max3_f32 v100, v100, v74, v75
	v_max3_f32 v100, v100, v76, v77
	v_max3_f32 v100, v100, v78, v79
	s_waitcnt lgkmcnt(0)
	v_mfma_f32_32x32x16_bf16 v[32:47], v[108:111], v[112:115], v[32:47]
	s_nop 2
	v_max3_f32 v100, v100, v48, v49
	v_max3_f32 v100, v100, v50, v51
	v_max3_f32 v100, v100, v52, v53
	v_max3_f32 v100, v100, v54, v55
	v_max3_f32 v100, v100, v56, v57
	v_max3_f32 v100, v100, v58, v59
	v_max3_f32 v100, v100, v60, v61
	v_mfma_f32_32x32x16_bf16 v[32:47], v[96:99], v[116:119], v[32:47]
	v_max3_f32 v100, v100, v62, v63
	s_nop 10
	v_max3_f32 v96, v100, v32, v33
	v_max3_f32 v96, v96, v34, v35
	v_max3_f32 v96, v96, v36, v37
	v_max3_f32 v96, v96, v38, v39
	v_max3_f32 v96, v96, v40, v41
	v_max3_f32 v96, v96, v42, v43
	v_max3_f32 v96, v96, v44, v45
	v_max3_f32 v96, v96, v46, v47
	v_mov_b32_e32 v97, v96
	s_nop 1
	v_permlane32_swap_b32_e32 v97, v96
	v_max_f32_e32 v96, v96, v97
	v_cmp_gt_f32_e32 vcc, v96, v210
	s_cbranch_vccz .LBB0_661
	s_nop 1
	v_cndmask_b32_e32 v96, 0, v96, vcc
	v_exp_f32_e64 v98, -v96
	s_nop 0
	v_pk_mul_f32 v[30:31], v[30:31], v[98:99] op_sel_hi:[1,0]
	v_pk_mul_f32 v[28:29], v[28:29], v[98:99] op_sel_hi:[1,0]
	v_pk_mul_f32 v[26:27], v[26:27], v[98:99] op_sel_hi:[1,0]
	v_pk_mul_f32 v[24:25], v[24:25], v[98:99] op_sel_hi:[1,0]
	v_pk_mul_f32 v[22:23], v[22:23], v[98:99] op_sel_hi:[1,0]
	v_pk_mul_f32 v[20:21], v[20:21], v[98:99] op_sel_hi:[1,0]
	v_pk_mul_f32 v[18:19], v[18:19], v[98:99] op_sel_hi:[1,0]
	v_pk_mul_f32 v[16:17], v[16:17], v[98:99] op_sel_hi:[1,0]
	v_pk_mul_f32 v[14:15], v[14:15], v[98:99] op_sel_hi:[1,0]
	v_pk_mul_f32 v[12:13], v[12:13], v[98:99] op_sel_hi:[1,0]
	v_pk_mul_f32 v[10:11], v[10:11], v[98:99] op_sel_hi:[1,0]
	v_pk_mul_f32 v[8:9], v[8:9], v[98:99] op_sel_hi:[1,0]
	v_pk_mul_f32 v[6:7], v[6:7], v[98:99] op_sel_hi:[1,0]
	v_pk_mul_f32 v[4:5], v[4:5], v[98:99] op_sel_hi:[1,0]
	v_pk_mul_f32 v[2:3], v[2:3], v[98:99] op_sel_hi:[1,0]
	v_pk_mul_f32 v[0:1], v[0:1], v[98:99] op_sel_hi:[1,0]
	v_mul_f32_e32 v149, v149, v98
	v_sub_f32_e32 v80, v80, v96
	v_sub_f32_e32 v81, v81, v96
	v_sub_f32_e32 v82, v82, v96
	v_sub_f32_e32 v83, v83, v96
	v_sub_f32_e32 v84, v84, v96
	v_sub_f32_e32 v85, v85, v96
	v_sub_f32_e32 v86, v86, v96
	v_sub_f32_e32 v87, v87, v96
	v_sub_f32_e32 v88, v88, v96
	v_sub_f32_e32 v89, v89, v96
	v_sub_f32_e32 v90, v90, v96
	v_sub_f32_e32 v91, v91, v96
	v_sub_f32_e32 v92, v92, v96
	v_sub_f32_e32 v93, v93, v96
	v_sub_f32_e32 v94, v94, v96
	v_sub_f32_e32 v95, v95, v96
	v_sub_f32_e32 v64, v64, v96
	v_sub_f32_e32 v65, v65, v96
	v_sub_f32_e32 v66, v66, v96
	v_sub_f32_e32 v67, v67, v96
	v_sub_f32_e32 v68, v68, v96
	v_sub_f32_e32 v69, v69, v96
	v_sub_f32_e32 v70, v70, v96
	v_sub_f32_e32 v71, v71, v96
	v_sub_f32_e32 v72, v72, v96
	v_sub_f32_e32 v73, v73, v96
	v_sub_f32_e32 v74, v74, v96
	v_sub_f32_e32 v75, v75, v96
	v_sub_f32_e32 v76, v76, v96
	v_sub_f32_e32 v77, v77, v96
	v_sub_f32_e32 v78, v78, v96
	v_sub_f32_e32 v79, v79, v96
	v_sub_f32_e32 v48, v48, v96
	v_sub_f32_e32 v49, v49, v96
	v_sub_f32_e32 v50, v50, v96
	v_sub_f32_e32 v51, v51, v96
	v_sub_f32_e32 v52, v52, v96
	v_sub_f32_e32 v53, v53, v96
	v_sub_f32_e32 v54, v54, v96
	v_sub_f32_e32 v55, v55, v96
	v_sub_f32_e32 v56, v56, v96
	v_sub_f32_e32 v57, v57, v96
	v_sub_f32_e32 v58, v58, v96
	v_sub_f32_e32 v59, v59, v96
	v_sub_f32_e32 v60, v60, v96
	v_sub_f32_e32 v61, v61, v96
	v_sub_f32_e32 v62, v62, v96
	v_sub_f32_e32 v63, v63, v96
	v_sub_f32_e32 v32, v32, v96
	v_sub_f32_e32 v33, v33, v96
	v_sub_f32_e32 v34, v34, v96
	v_sub_f32_e32 v35, v35, v96
	v_sub_f32_e32 v36, v36, v96
	v_sub_f32_e32 v37, v37, v96
	v_sub_f32_e32 v38, v38, v96
	v_sub_f32_e32 v39, v39, v96
	v_sub_f32_e32 v40, v40, v96
	v_sub_f32_e32 v41, v41, v96
	v_sub_f32_e32 v42, v42, v96
	v_sub_f32_e32 v43, v43, v96
	v_sub_f32_e32 v44, v44, v96
	v_sub_f32_e32 v45, v45, v96
	v_sub_f32_e32 v46, v46, v96
	v_sub_f32_e32 v47, v47, v96

.LBB0_665:
	s_mov_b32 s1, s98
	v_add3_u32 v171, s1, v169, v170
	ds_read_b128 v[32:35], v171
	ds_read_b128 v[174:177], v171 offset:32
	s_waitcnt lgkmcnt(1)
	v_mfma_f32_32x32x16_bf16 v[80:95], v[32:35], v[108:111], v[194:209]
	ds_read_b128 v[32:35], v171 offset:6656
	ds_read_b128 v[178:181], v171 offset:6688
	s_waitcnt lgkmcnt(1)
	v_mfma_f32_32x32x16_bf16 v[64:79], v[32:35], v[108:111], v[194:209]
	ds_read_b128 v[32:35], v171 offset:13312
	ds_read_b128 v[182:185], v171 offset:13344
	s_waitcnt lgkmcnt(1)
	v_mfma_f32_32x32x16_bf16 v[48:63], v[32:35], v[108:111], v[194:209]
	ds_read_b128 v[32:35], v171 offset:19968
	ds_read_b128 v[186:189], v171 offset:20000
	v_mfma_f32_32x32x16_bf16 v[80:95], v[174:177], v[104:107], v[80:95]
	s_waitcnt lgkmcnt(1)
	v_mfma_f32_32x32x16_bf16 v[32:47], v[32:35], v[108:111], v[194:209]
	v_mfma_f32_32x32x16_bf16 v[64:79], v[178:181], v[104:107], v[64:79]
	ds_read_b128 v[174:177], v171 offset:64
	ds_read_b128 v[178:181], v171 offset:96
	v_mfma_f32_32x32x16_bf16 v[48:63], v[182:185], v[104:107], v[48:63]
	s_waitcnt lgkmcnt(1)
	v_mfma_f32_32x32x16_bf16 v[80:95], v[174:177], v[100:103], v[80:95]
	ds_read_b128 v[174:177], v171 offset:6720
	ds_read_b128 v[182:185], v171 offset:6752
	v_mfma_f32_32x32x16_bf16 v[32:47], v[186:189], v[104:107], v[32:47]
	s_waitcnt lgkmcnt(1)
	v_mfma_f32_32x32x16_bf16 v[64:79], v[174:177], v[100:103], v[64:79]
	ds_read_b128 v[174:177], v171 offset:13376
	ds_read_b128 v[186:189], v171 offset:13408
	s_waitcnt lgkmcnt(1)
	v_mfma_f32_32x32x16_bf16 v[48:63], v[174:177], v[100:103], v[48:63]
	ds_read_b128 v[174:177], v171 offset:20032
	ds_read_b128 v[190:193], v171 offset:20064
	v_mfma_f32_32x32x16_bf16 v[80:95], v[178:181], v[96:99], v[80:95]
	s_waitcnt lgkmcnt(1)
	v_mfma_f32_32x32x16_bf16 v[32:47], v[174:177], v[100:103], v[32:47]
	ds_read_b128 v[174:177], v171 offset:128
	ds_read_b128 v[178:181], v171 offset:160
	s_waitcnt lgkmcnt(1)
	v_mfma_f32_32x32x16_bf16 v[80:95], v[174:177], v[112:115], v[80:95]
	v_mfma_f32_32x32x16_bf16 v[64:79], v[182:185], v[96:99], v[64:79]
	ds_read_b128 v[174:177], v171 offset:6784
	ds_read_b128 v[182:185], v171 offset:6816
	v_mfma_f32_32x32x16_bf16 v[48:63], v[186:189], v[96:99], v[48:63]
	s_waitcnt lgkmcnt(2)
	v_mfma_f32_32x32x16_bf16 v[80:95], v[178:181], v[116:119], v[80:95]
	s_waitcnt lgkmcnt(1)
	v_mfma_f32_32x32x16_bf16 v[64:79], v[174:177], v[112:115], v[64:79]
	ds_read_b128 v[174:177], v171 offset:13440
	ds_read_b128 v[186:189], v171 offset:13472
	s_nop 7
	v_max_f32_e32 v173, v80, v80
	s_waitcnt lgkmcnt(1)
	v_mfma_f32_32x32x16_bf16 v[48:63], v[174:177], v[112:115], v[48:63]
	ds_read_b128 v[174:177], v171 offset:20096
	ds_read_b128 v[178:181], v171 offset:20128
	v_max_f32_e32 v171, v81, v81
	v_max_f32_e32 v171, v173, v171
	v_max3_f32 v171, v171, v82, v83
	v_max3_f32 v171, v171, v84, v85
	v_max3_f32 v171, v171, v86, v87
	v_max3_f32 v171, v171, v88, v89
	v_mfma_f32_32x32x16_bf16 v[32:47], v[190:193], v[96:99], v[32:47]
	v_max3_f32 v171, v171, v90, v91
	v_max3_f32 v171, v171, v92, v93
	v_max3_f32 v171, v171, v94, v95
	v_mfma_f32_32x32x16_bf16 v[64:79], v[182:185], v[116:119], v[64:79]
	s_waitcnt lgkmcnt(2)
	v_mfma_f32_32x32x16_bf16 v[48:63], v[186:189], v[116:119], v[48:63]
	s_nop 9
	v_max3_f32 v171, v171, v64, v65
	v_max3_f32 v171, v171, v66, v67
	v_max3_f32 v171, v171, v68, v69
	v_max3_f32 v171, v171, v70, v71
	v_max3_f32 v171, v171, v72, v73
	v_max3_f32 v171, v171, v74, v75
	v_max3_f32 v171, v171, v76, v77
	s_waitcnt lgkmcnt(1)
	v_mfma_f32_32x32x16_bf16 v[32:47], v[174:177], v[112:115], v[32:47]
	v_max3_f32 v171, v171, v78, v79
	v_max3_f32 v171, v171, v48, v49
	v_max3_f32 v171, v171, v50, v51
	v_max3_f32 v171, v171, v52, v53
	v_max3_f32 v171, v171, v54, v55
	v_max3_f32 v171, v171, v56, v57
	v_max3_f32 v171, v171, v58, v59
	s_waitcnt lgkmcnt(0)
	v_mfma_f32_32x32x16_bf16 v[32:47], v[178:181], v[116:119], v[32:47]
	v_max3_f32 v171, v171, v60, v61
	v_max3_f32 v171, v171, v62, v63
	s_nop 9
	v_max3_f32 v171, v171, v32, v33
	v_max3_f32 v171, v171, v34, v35
	v_max3_f32 v171, v171, v36, v37
	v_max3_f32 v171, v171, v38, v39
	v_max3_f32 v171, v171, v40, v41
	v_max3_f32 v171, v171, v42, v43
	v_max3_f32 v171, v171, v44, v45
	v_max3_f32 v171, v171, v46, v47
	v_mov_b32_e32 v173, v171
	s_nop 1
	v_permlane32_swap_b32_e32 v173, v171
	v_max_f32_e32 v171, v171, v173
	v_cmp_gt_f32_e32 vcc, v171, v210
	s_cbranch_vccz .LBB0_668
	s_nop 1
	v_cndmask_b32_e32 v171, 0, v171, vcc
	v_exp_f32_e64 v172, -v171
	v_sub_f32_e32 v194, v194, v171
	v_sub_f32_e32 v195, v195, v171
	v_sub_f32_e32 v196, v196, v171
	v_sub_f32_e32 v197, v197, v171
	v_sub_f32_e32 v198, v198, v171
	v_sub_f32_e32 v199, v199, v171
	v_sub_f32_e32 v200, v200, v171
	v_sub_f32_e32 v201, v201, v171
	v_sub_f32_e32 v202, v202, v171
	v_sub_f32_e32 v203, v203, v171
	v_sub_f32_e32 v204, v204, v171
	v_sub_f32_e32 v205, v205, v171
	v_sub_f32_e32 v206, v206, v171
	v_sub_f32_e32 v207, v207, v171
	v_sub_f32_e32 v208, v208, v171
	v_sub_f32_e32 v209, v209, v171
	v_pk_mul_f32 v[30:31], v[30:31], v[172:173] op_sel_hi:[1,0]
	v_pk_mul_f32 v[28:29], v[28:29], v[172:173] op_sel_hi:[1,0]
	v_pk_mul_f32 v[26:27], v[26:27], v[172:173] op_sel_hi:[1,0]
	v_pk_mul_f32 v[24:25], v[24:25], v[172:173] op_sel_hi:[1,0]
	v_pk_mul_f32 v[22:23], v[22:23], v[172:173] op_sel_hi:[1,0]
	v_pk_mul_f32 v[20:21], v[20:21], v[172:173] op_sel_hi:[1,0]
	v_pk_mul_f32 v[18:19], v[18:19], v[172:173] op_sel_hi:[1,0]
	v_pk_mul_f32 v[16:17], v[16:17], v[172:173] op_sel_hi:[1,0]
	v_pk_mul_f32 v[14:15], v[14:15], v[172:173] op_sel_hi:[1,0]
	v_pk_mul_f32 v[12:13], v[12:13], v[172:173] op_sel_hi:[1,0]
	v_pk_mul_f32 v[10:11], v[10:11], v[172:173] op_sel_hi:[1,0]
	v_pk_mul_f32 v[8:9], v[8:9], v[172:173] op_sel_hi:[1,0]
	v_pk_mul_f32 v[6:7], v[6:7], v[172:173] op_sel_hi:[1,0]
	v_pk_mul_f32 v[4:5], v[4:5], v[172:173] op_sel_hi:[1,0]
	v_pk_mul_f32 v[2:3], v[2:3], v[172:173] op_sel_hi:[1,0]
	v_pk_mul_f32 v[0:1], v[0:1], v[172:173] op_sel_hi:[1,0]
	v_mul_f32_e32 v149, v149, v172
	v_sub_f32_e32 v80, v80, v171
	v_sub_f32_e32 v81, v81, v171
	v_sub_f32_e32 v82, v82, v171
	v_sub_f32_e32 v83, v83, v171
	v_sub_f32_e32 v84, v84, v171
	v_sub_f32_e32 v85, v85, v171
	v_sub_f32_e32 v86, v86, v171
	v_sub_f32_e32 v87, v87, v171
	v_sub_f32_e32 v88, v88, v171
	v_sub_f32_e32 v89, v89, v171
	v_sub_f32_e32 v90, v90, v171
	v_sub_f32_e32 v91, v91, v171
	v_sub_f32_e32 v92, v92, v171
	v_sub_f32_e32 v93, v93, v171
	v_sub_f32_e32 v94, v94, v171
	v_sub_f32_e32 v95, v95, v171
	v_sub_f32_e32 v64, v64, v171
	v_sub_f32_e32 v65, v65, v171
	v_sub_f32_e32 v66, v66, v171
	v_sub_f32_e32 v67, v67, v171
	v_sub_f32_e32 v68, v68, v171
	v_sub_f32_e32 v69, v69, v171
	v_sub_f32_e32 v70, v70, v171
	v_sub_f32_e32 v71, v71, v171
	v_sub_f32_e32 v72, v72, v171
	v_sub_f32_e32 v73, v73, v171
	v_sub_f32_e32 v74, v74, v171
	v_sub_f32_e32 v75, v75, v171
	v_sub_f32_e32 v76, v76, v171
	v_sub_f32_e32 v77, v77, v171
	v_sub_f32_e32 v78, v78, v171
	v_sub_f32_e32 v79, v79, v171
	v_sub_f32_e32 v48, v48, v171
	v_sub_f32_e32 v49, v49, v171
	v_sub_f32_e32 v50, v50, v171
	v_sub_f32_e32 v51, v51, v171
	v_sub_f32_e32 v52, v52, v171
	v_sub_f32_e32 v53, v53, v171
	v_sub_f32_e32 v54, v54, v171
	v_sub_f32_e32 v55, v55, v171
	v_sub_f32_e32 v56, v56, v171
	v_sub_f32_e32 v57, v57, v171
	v_sub_f32_e32 v58, v58, v171
	v_sub_f32_e32 v59, v59, v171
	v_sub_f32_e32 v60, v60, v171
	v_sub_f32_e32 v61, v61, v171
	v_sub_f32_e32 v62, v62, v171
	v_sub_f32_e32 v63, v63, v171
	v_sub_f32_e32 v32, v32, v171
	v_sub_f32_e32 v33, v33, v171
	v_sub_f32_e32 v34, v34, v171
	v_sub_f32_e32 v35, v35, v171
	v_sub_f32_e32 v36, v36, v171
	v_sub_f32_e32 v37, v37, v171
	v_sub_f32_e32 v38, v38, v171
	v_sub_f32_e32 v39, v39, v171
	v_sub_f32_e32 v40, v40, v171
	v_sub_f32_e32 v41, v41, v171
	v_sub_f32_e32 v42, v42, v171
	v_sub_f32_e32 v43, v43, v171
	v_sub_f32_e32 v44, v44, v171
	v_sub_f32_e32 v45, v45, v171
	v_sub_f32_e32 v46, v46, v171
	v_sub_f32_e32 v47, v47, v171
	v_mov_b32_e32 v210, 0x41000000

.LBB0_2129:
	s_mov_b32 s4, s98
	v_add3_u32 v171, s4, v169, v170
	ds_read_b128 v[32:35], v171
	ds_read_b128 v[174:177], v171 offset:32
	s_waitcnt lgkmcnt(1)
	v_mfma_f32_32x32x16_bf16 v[80:95], v[32:35], v[108:111], v[194:209]
	ds_read_b128 v[32:35], v171 offset:6656
	ds_read_b128 v[178:181], v171 offset:6688
	s_waitcnt lgkmcnt(1)
	v_mfma_f32_32x32x16_bf16 v[64:79], v[32:35], v[108:111], v[194:209]
	ds_read_b128 v[32:35], v171 offset:13312
	ds_read_b128 v[182:185], v171 offset:13344
	s_waitcnt lgkmcnt(1)
	v_mfma_f32_32x32x16_bf16 v[48:63], v[32:35], v[108:111], v[194:209]
	ds_read_b128 v[32:35], v171 offset:19968
	ds_read_b128 v[186:189], v171 offset:20000
	v_mfma_f32_32x32x16_bf16 v[80:95], v[174:177], v[104:107], v[80:95]
	s_waitcnt lgkmcnt(1)
	v_mfma_f32_32x32x16_bf16 v[32:47], v[32:35], v[108:111], v[194:209]
	v_mfma_f32_32x32x16_bf16 v[64:79], v[178:181], v[104:107], v[64:79]
	ds_read_b128 v[174:177], v171 offset:64
	ds_read_b128 v[178:181], v171 offset:96
	v_mfma_f32_32x32x16_bf16 v[48:63], v[182:185], v[104:107], v[48:63]
	s_waitcnt lgkmcnt(1)
	v_mfma_f32_32x32x16_bf16 v[80:95], v[174:177], v[100:103], v[80:95]
	ds_read_b128 v[174:177], v171 offset:6720
	ds_read_b128 v[182:185], v171 offset:6752
	v_mfma_f32_32x32x16_bf16 v[32:47], v[186:189], v[104:107], v[32:47]
	s_waitcnt lgkmcnt(1)
	v_mfma_f32_32x32x16_bf16 v[64:79], v[174:177], v[100:103], v[64:79]
	ds_read_b128 v[174:177], v171 offset:13376
	ds_read_b128 v[186:189], v171 offset:13408
	s_waitcnt lgkmcnt(1)
	v_mfma_f32_32x32x16_bf16 v[48:63], v[174:177], v[100:103], v[48:63]
	ds_read_b128 v[174:177], v171 offset:20032
	ds_read_b128 v[190:193], v171 offset:20064
	v_mfma_f32_32x32x16_bf16 v[80:95], v[178:181], v[96:99], v[80:95]
	s_waitcnt lgkmcnt(1)
	v_mfma_f32_32x32x16_bf16 v[32:47], v[174:177], v[100:103], v[32:47]
	ds_read_b128 v[174:177], v171 offset:128
	ds_read_b128 v[178:181], v171 offset:160
	s_waitcnt lgkmcnt(1)
	v_mfma_f32_32x32x16_bf16 v[80:95], v[174:177], v[112:115], v[80:95]
	v_mfma_f32_32x32x16_bf16 v[64:79], v[182:185], v[96:99], v[64:79]
	ds_read_b128 v[174:177], v171 offset:6784
	ds_read_b128 v[182:185], v171 offset:6816
	v_mfma_f32_32x32x16_bf16 v[48:63], v[186:189], v[96:99], v[48:63]
	s_waitcnt lgkmcnt(2)
	v_mfma_f32_32x32x16_bf16 v[80:95], v[178:181], v[116:119], v[80:95]
	s_waitcnt lgkmcnt(1)
	v_mfma_f32_32x32x16_bf16 v[64:79], v[174:177], v[112:115], v[64:79]
	ds_read_b128 v[174:177], v171 offset:13440
	ds_read_b128 v[186:189], v171 offset:13472
	s_nop 7
	v_max_f32_e32 v173, v80, v80
	s_waitcnt lgkmcnt(1)
	v_mfma_f32_32x32x16_bf16 v[48:63], v[174:177], v[112:115], v[48:63]
	ds_read_b128 v[174:177], v171 offset:20096
	ds_read_b128 v[178:181], v171 offset:20128
	v_max_f32_e32 v171, v81, v81
	v_max_f32_e32 v171, v173, v171
	v_max3_f32 v171, v171, v82, v83
	v_max3_f32 v171, v171, v84, v85
	v_max3_f32 v171, v171, v86, v87
	v_max3_f32 v171, v171, v88, v89
	v_mfma_f32_32x32x16_bf16 v[32:47], v[190:193], v[96:99], v[32:47]
	v_max3_f32 v171, v171, v90, v91
	v_max3_f32 v171, v171, v92, v93
	v_max3_f32 v171, v171, v94, v95
	v_mfma_f32_32x32x16_bf16 v[64:79], v[182:185], v[116:119], v[64:79]
	s_waitcnt lgkmcnt(2)
	v_mfma_f32_32x32x16_bf16 v[48:63], v[186:189], v[116:119], v[48:63]
	s_nop 9
	v_max3_f32 v171, v171, v64, v65
	v_max3_f32 v171, v171, v66, v67
	v_max3_f32 v171, v171, v68, v69
	v_max3_f32 v171, v171, v70, v71
	v_max3_f32 v171, v171, v72, v73
	v_max3_f32 v171, v171, v74, v75
	v_max3_f32 v171, v171, v76, v77
	s_waitcnt lgkmcnt(1)
	v_mfma_f32_32x32x16_bf16 v[32:47], v[174:177], v[112:115], v[32:47]
	v_max3_f32 v171, v171, v78, v79
	v_max3_f32 v171, v171, v48, v49
	v_max3_f32 v171, v171, v50, v51
	v_max3_f32 v171, v171, v52, v53
	v_max3_f32 v171, v171, v54, v55
	v_max3_f32 v171, v171, v56, v57
	v_max3_f32 v171, v171, v58, v59
	s_waitcnt lgkmcnt(0)
	v_mfma_f32_32x32x16_bf16 v[32:47], v[178:181], v[116:119], v[32:47]
	v_max3_f32 v171, v171, v60, v61
	v_max3_f32 v171, v171, v62, v63
	s_nop 9
	v_max3_f32 v171, v171, v32, v33
	v_max3_f32 v171, v171, v34, v35
	v_max3_f32 v171, v171, v36, v37
	v_max3_f32 v171, v171, v38, v39
	v_max3_f32 v171, v171, v40, v41
	v_max3_f32 v171, v171, v42, v43
	v_max3_f32 v171, v171, v44, v45
	v_max3_f32 v171, v171, v46, v47
	v_mov_b32_e32 v173, v171
	s_nop 1
	v_permlane32_swap_b32_e32 v173, v171
	v_max_f32_e32 v171, v171, v173
	v_cmp_gt_f32_e32 vcc, v171, v210
	s_cbranch_vccz .LBB0_2132
	s_nop 1
	v_cndmask_b32_e32 v171, 0, v171, vcc
	v_exp_f32_e64 v172, -v171
	v_sub_f32_e32 v194, v194, v171
	v_sub_f32_e32 v195, v195, v171
	v_sub_f32_e32 v196, v196, v171
	v_sub_f32_e32 v197, v197, v171
	v_sub_f32_e32 v198, v198, v171
	v_sub_f32_e32 v199, v199, v171
	v_sub_f32_e32 v200, v200, v171
	v_sub_f32_e32 v201, v201, v171
	v_sub_f32_e32 v202, v202, v171
	v_sub_f32_e32 v203, v203, v171
	v_sub_f32_e32 v204, v204, v171
	v_sub_f32_e32 v205, v205, v171
	v_sub_f32_e32 v206, v206, v171
	v_sub_f32_e32 v207, v207, v171
	v_sub_f32_e32 v208, v208, v171
	v_sub_f32_e32 v209, v209, v171
	v_pk_mul_f32 v[30:31], v[30:31], v[172:173] op_sel_hi:[1,0]
	v_pk_mul_f32 v[28:29], v[28:29], v[172:173] op_sel_hi:[1,0]
	v_pk_mul_f32 v[26:27], v[26:27], v[172:173] op_sel_hi:[1,0]
	v_pk_mul_f32 v[24:25], v[24:25], v[172:173] op_sel_hi:[1,0]
	v_pk_mul_f32 v[22:23], v[22:23], v[172:173] op_sel_hi:[1,0]
	v_pk_mul_f32 v[20:21], v[20:21], v[172:173] op_sel_hi:[1,0]
	v_pk_mul_f32 v[18:19], v[18:19], v[172:173] op_sel_hi:[1,0]
	v_pk_mul_f32 v[16:17], v[16:17], v[172:173] op_sel_hi:[1,0]
	v_pk_mul_f32 v[14:15], v[14:15], v[172:173] op_sel_hi:[1,0]
	v_pk_mul_f32 v[12:13], v[12:13], v[172:173] op_sel_hi:[1,0]
	v_pk_mul_f32 v[10:11], v[10:11], v[172:173] op_sel_hi:[1,0]
	v_pk_mul_f32 v[8:9], v[8:9], v[172:173] op_sel_hi:[1,0]
	v_pk_mul_f32 v[6:7], v[6:7], v[172:173] op_sel_hi:[1,0]
	v_pk_mul_f32 v[4:5], v[4:5], v[172:173] op_sel_hi:[1,0]
	v_pk_mul_f32 v[2:3], v[2:3], v[172:173] op_sel_hi:[1,0]
	v_pk_mul_f32 v[0:1], v[0:1], v[172:173] op_sel_hi:[1,0]
	v_mul_f32_e32 v149, v149, v172
	v_sub_f32_e32 v80, v80, v171
	v_sub_f32_e32 v81, v81, v171
	v_sub_f32_e32 v82, v82, v171
	v_sub_f32_e32 v83, v83, v171
	v_sub_f32_e32 v84, v84, v171
	v_sub_f32_e32 v85, v85, v171
	v_sub_f32_e32 v86, v86, v171
	v_sub_f32_e32 v87, v87, v171
	v_sub_f32_e32 v88, v88, v171
	v_sub_f32_e32 v89, v89, v171
	v_sub_f32_e32 v90, v90, v171
	v_sub_f32_e32 v91, v91, v171
	v_sub_f32_e32 v92, v92, v171
	v_sub_f32_e32 v93, v93, v171
	v_sub_f32_e32 v94, v94, v171
	v_sub_f32_e32 v95, v95, v171
	v_sub_f32_e32 v64, v64, v171
	v_sub_f32_e32 v65, v65, v171
	v_sub_f32_e32 v66, v66, v171
	v_sub_f32_e32 v67, v67, v171
	v_sub_f32_e32 v68, v68, v171
	v_sub_f32_e32 v69, v69, v171
	v_sub_f32_e32 v70, v70, v171
	v_sub_f32_e32 v71, v71, v171
	v_sub_f32_e32 v72, v72, v171
	v_sub_f32_e32 v73, v73, v171
	v_sub_f32_e32 v74, v74, v171
	v_sub_f32_e32 v75, v75, v171
	v_sub_f32_e32 v76, v76, v171
	v_sub_f32_e32 v77, v77, v171
	v_sub_f32_e32 v78, v78, v171
	v_sub_f32_e32 v79, v79, v171
	v_sub_f32_e32 v48, v48, v171
	v_sub_f32_e32 v49, v49, v171
	v_sub_f32_e32 v50, v50, v171
	v_sub_f32_e32 v51, v51, v171
	v_sub_f32_e32 v52, v52, v171
	v_sub_f32_e32 v53, v53, v171
	v_sub_f32_e32 v54, v54, v171
	v_sub_f32_e32 v55, v55, v171
	v_sub_f32_e32 v56, v56, v171
	v_sub_f32_e32 v57, v57, v171
	v_sub_f32_e32 v58, v58, v171
	v_sub_f32_e32 v59, v59, v171
	v_sub_f32_e32 v60, v60, v171
	v_sub_f32_e32 v61, v61, v171
	v_sub_f32_e32 v62, v62, v171
	v_sub_f32_e32 v63, v63, v171
	v_sub_f32_e32 v32, v32, v171
	v_sub_f32_e32 v33, v33, v171
	v_sub_f32_e32 v34, v34, v171
	v_sub_f32_e32 v35, v35, v171
	v_sub_f32_e32 v36, v36, v171
	v_sub_f32_e32 v37, v37, v171
	v_sub_f32_e32 v38, v38, v171
	v_sub_f32_e32 v39, v39, v171
	v_sub_f32_e32 v40, v40, v171
	v_sub_f32_e32 v41, v41, v171
	v_sub_f32_e32 v42, v42, v171
	v_sub_f32_e32 v43, v43, v171
	v_sub_f32_e32 v44, v44, v171
	v_sub_f32_e32 v45, v45, v171
	v_sub_f32_e32 v46, v46, v171
	v_sub_f32_e32 v47, v47, v171
	v_mov_b32_e32 v210, 0x41000000
